# sample_ssd head loop: z-gate load hoisted to iteration top, mid-loop vmcnt(0) relaxed to counted wait so next-head state prefetch stays in flight
# speedup vs baseline: 1.0136x; 1.0039x over previous
; __device__ __forceinline__ void sample_ssd(const Params& p, unsigned char* smem, int job) {
;     ...
;         const float cl = cum[7], dec = __expf(cl);
;         float xw[8];
; #pragma unroll
;         for (int s = 0; s < 8; ++s) xw[s] = __expf(cl - cum[s]) * dtv[s] * xall[s * 1024 + hh * 64 + pp];
; #pragma unroll
;         for (int i = 0; i < 4; ++i) {
;             f32x4 acc = s0[i] * dec;
; #pragma unroll
;             for (int s = 0; s < 8; ++s) acc += xw[s] * *(const f32x4*)(Bc + s * 128 + nq * 4 + 32 * i);
;             __builtin_nontemporal_store(acc, (f32x4*)(p.out + O_S_SSD + soff + 32 * i));
;         }
.LBB0_677:
	s_or_b64 exec, exec, s[36:37]
	v_sub_f32_e32 v60, v87, v93
	v_mul_f32_e32 v60, 0x3fb8aa3b, v60
	v_exp_f32_e32 v60, v60
	s_waitcnt lgkmcnt(0)
	v_mul_f32_e32 v61, 0x3fb8aa3b, v87
	v_add_u32_e32 v84, 0x100, v84
	v_add_u32_e32 v85, 0x100, v85
	v_mul_f32_e32 v40, v40, v60
	v_mul_f32_e32 v66, v40, v62
	v_sub_f32_e32 v40, v87, v92
	v_mul_f32_e32 v40, 0x3fb8aa3b, v40
	v_exp_f32_e32 v40, v40
	v_lshl_add_u64 v[52:53], v[52:53], 0, s[34:35]
	v_lshl_add_u64 v[54:55], v[54:55], 0, s[34:35]
	v_mul_f32_e32 v40, v41, v40
	v_mul_f32_e32 v62, v40, v63
	v_sub_f32_e32 v40, v87, v91
	v_mul_f32_e32 v40, 0x3fb8aa3b, v40
	v_exp_f32_e32 v40, v40
	s_nop 0
	v_mul_f32_e32 v40, v42, v40
	v_mul_f32_e32 v64, v40, v64
	v_sub_f32_e32 v40, v87, v90
	v_mul_f32_e32 v40, 0x3fb8aa3b, v40
	v_exp_f32_e32 v40, v40
	s_nop 0
	v_mul_f32_e32 v40, v43, v40
	v_mul_f32_e32 v42, v40, v65
	v_sub_f32_e32 v40, v87, v89
	v_mul_f32_e32 v40, 0x3fb8aa3b, v40
	v_exp_f32_e32 v40, v40
	s_nop 0
	v_mul_f32_e32 v36, v36, v40
	v_mul_f32_e32 v60, v36, v68
	v_sub_f32_e32 v36, v87, v88
	v_mul_f32_e32 v36, 0x3fb8aa3b, v36
	v_exp_f32_e32 v36, v36
	v_exp_f32_e32 v68, v61
	v_mul_f32_e32 v36, v37, v36
	v_mul_f32_e32 v40, v36, v69
	v_sub_f32_e32 v36, v87, v86
	v_mul_f32_e32 v36, 0x3fb8aa3b, v36
	v_exp_f32_e32 v36, v36
	ds_read_b128 v[86:89], v73
	v_mul_f32_e32 v36, v38, v36
	v_mul_f32_e32 v38, v36, v70
	v_exp_f32_e32 v36, v110
	s_waitcnt lgkmcnt(0)
	v_pk_mul_f32 v[86:87], v[86:87], v[66:67] op_sel_hi:[1,0]
	v_mul_f32_e32 v36, v39, v36
	v_mul_f32_e32 v36, v36, v71
	v_pk_mul_f32 v[70:71], v[88:89], v[66:67] op_sel_hi:[1,0]
	v_pk_fma_f32 v[86:87], v[32:33], v[68:69], v[86:87] op_sel_hi:[1,0,1]
	v_pk_fma_f32 v[70:71], v[34:35], v[68:69], v[70:71] op_sel_hi:[1,0,1]
	ds_read_b128 v[32:35], v73 offset:512
	s_waitcnt lgkmcnt(0)
	v_pk_fma_f32 v[70:71], v[34:35], v[62:63], v[70:71] op_sel_hi:[1,0,1]
	v_pk_fma_f32 v[86:87], v[32:33], v[62:63], v[86:87] op_sel_hi:[1,0,1]
	ds_read_b128 v[32:35], v73 offset:1024
	s_waitcnt lgkmcnt(0)
	v_pk_fma_f32 v[70:71], v[64:65], v[34:35], v[70:71] op_sel_hi:[0,1,1]
	v_pk_fma_f32 v[86:87], v[64:65], v[32:33], v[86:87] op_sel_hi:[0,1,1]
	ds_read_b128 v[32:35], v73 offset:1536
	s_waitcnt lgkmcnt(0)
	v_pk_fma_f32 v[70:71], v[42:43], v[34:35], v[70:71] op_sel_hi:[0,1,1]
	v_pk_fma_f32 v[86:87], v[42:43], v[32:33], v[86:87] op_sel_hi:[0,1,1]
	ds_read_b128 v[32:35], v73 offset:2048
	s_waitcnt lgkmcnt(0)
	v_pk_fma_f32 v[70:71], v[60:61], v[34:35], v[70:71] op_sel_hi:[0,1,1]
	v_pk_fma_f32 v[86:87], v[60:61], v[32:33], v[86:87] op_sel_hi:[0,1,1]
	ds_read_b128 v[32:35], v73 offset:2560
	s_waitcnt lgkmcnt(0)
	v_pk_fma_f32 v[70:71], v[40:41], v[34:35], v[70:71] op_sel_hi:[0,1,1]
	v_pk_fma_f32 v[86:87], v[40:41], v[32:33], v[86:87] op_sel_hi:[0,1,1]
	ds_read_b128 v[32:35], v73 offset:3072
	s_waitcnt lgkmcnt(0)
	v_pk_fma_f32 v[70:71], v[38:39], v[34:35], v[70:71] op_sel_hi:[0,1,1]
	v_pk_fma_f32 v[86:87], v[38:39], v[32:33], v[86:87] op_sel_hi:[0,1,1]
	ds_read_b128 v[32:35], v73 offset:3584
	s_waitcnt lgkmcnt(0)
	v_pk_fma_f32 v[88:89], v[36:37], v[34:35], v[70:71] op_sel_hi:[0,1,1]
	v_pk_fma_f32 v[86:87], v[36:37], v[32:33], v[86:87] op_sel_hi:[0,1,1]
	v_lshl_add_u64 v[32:33], v[58:59], 0, s[92:93]
	global_store_dwordx4 v[32:33], v[86:89], off offset:-256 nt
	ds_read_b128 v[86:89], v73 offset:128
	s_add_u32 s92, s92, 0x8000
	s_addc_u32 s93, s93, 0
	s_add_i32 s33, s33, 32
	s_add_u32 s86, s86, 4
	s_waitcnt lgkmcnt(0)
	v_pk_mul_f32 v[34:35], v[66:67], v[88:89] op_sel_hi:[0,1]
	v_pk_mul_f32 v[70:71], v[66:67], v[86:87] op_sel_hi:[0,1]
	v_pk_fma_f32 v[70:71], v[28:29], v[68:69], v[70:71] op_sel_hi:[1,0,1]
	v_pk_fma_f32 v[34:35], v[30:31], v[68:69], v[34:35] op_sel_hi:[1,0,1]
	ds_read_b128 v[28:31], v73 offset:640
	s_addc_u32 s87, s87, 0
	s_add_u32 s88, s88, 4
	s_addc_u32 s89, s89, 0
	s_cmp_eq_u32 s92, 0x78000
	s_waitcnt lgkmcnt(0)
	v_pk_fma_f32 v[34:35], v[62:63], v[30:31], v[34:35] op_sel_hi:[0,1,1]
	v_pk_fma_f32 v[70:71], v[62:63], v[28:29], v[70:71] op_sel_hi:[0,1,1]
	ds_read_b128 v[28:31], v73 offset:1152
	s_waitcnt lgkmcnt(0)
	v_pk_fma_f32 v[34:35], v[64:65], v[30:31], v[34:35] op_sel_hi:[0,1,1]
	v_pk_fma_f32 v[70:71], v[64:65], v[28:29], v[70:71] op_sel_hi:[0,1,1]
	ds_read_b128 v[28:31], v73 offset:1664
	s_waitcnt lgkmcnt(0)
	v_pk_fma_f32 v[34:35], v[42:43], v[30:31], v[34:35] op_sel_hi:[0,1,1]
	v_pk_fma_f32 v[70:71], v[42:43], v[28:29], v[70:71] op_sel_hi:[0,1,1]
	ds_read_b128 v[28:31], v73 offset:2176
	s_waitcnt lgkmcnt(0)
	v_pk_fma_f32 v[34:35], v[60:61], v[30:31], v[34:35] op_sel_hi:[0,1,1]
	v_pk_fma_f32 v[70:71], v[60:61], v[28:29], v[70:71] op_sel_hi:[0,1,1]
	ds_read_b128 v[28:31], v73 offset:2688
	s_waitcnt lgkmcnt(0)
	v_pk_fma_f32 v[34:35], v[40:41], v[30:31], v[34:35] op_sel_hi:[0,1,1]
	v_pk_fma_f32 v[70:71], v[40:41], v[28:29], v[70:71] op_sel_hi:[0,1,1]
	ds_read_b128 v[28:31], v73 offset:3200
	s_waitcnt lgkmcnt(0)
	v_pk_fma_f32 v[34:35], v[38:39], v[30:31], v[34:35] op_sel_hi:[0,1,1]
	v_pk_fma_f32 v[70:71], v[38:39], v[28:29], v[70:71] op_sel_hi:[0,1,1]
	ds_read_b128 v[28:31], v73 offset:3712
	s_waitcnt lgkmcnt(0)
	v_pk_fma_f32 v[30:31], v[36:37], v[30:31], v[34:35] op_sel_hi:[0,1,1]
	v_pk_fma_f32 v[28:29], v[36:37], v[28:29], v[70:71] op_sel_hi:[0,1,1]
	global_store_dwordx4 v[32:33], v[28:31], off offset:-128 nt
	ds_read_b128 v[28:31], v73 offset:256
	s_waitcnt lgkmcnt(0)
	v_pk_mul_f32 v[30:31], v[66:67], v[30:31] op_sel_hi:[0,1]
	v_pk_mul_f32 v[28:29], v[66:67], v[28:29] op_sel_hi:[0,1]
	v_pk_fma_f32 v[28:29], v[24:25], v[68:69], v[28:29] op_sel_hi:[1,0,1]
	v_pk_fma_f32 v[30:31], v[26:27], v[68:69], v[30:31] op_sel_hi:[1,0,1]
	ds_read_b128 v[24:27], v73 offset:768
	s_waitcnt lgkmcnt(0)
; __device__ __forceinline__ void sample_ssd(const Params& p, unsigned char* smem, int job) {
;     ...
;     for (int hh = 0; hh < 16; ++hh) {
;         const int h = g * 16 + hh;
;         const float A_h = -__expf(p.in[14][h]), D_h = p.in[15][h];
;         float dtv[8], cum[8];
;         { float run = 0.f;
; #pragma unroll
;           for (int t = 0; t < 8; ++t) { dtv[t] = dts[hh * 8 + t]; run += dtv[t] * A_h; cum[t] = run; } }
;         const size_t soff = ((size_t)(b * 32 + h) * 64 + pp) * 128 + nq * 4;
;         f32x4 s0[4];
; #pragma unroll
;         for (int i = 0; i < 4; ++i) s0[i] = snext[i];
;         if (hh + 1 < 16) {
; #pragma unroll
;             for (int i = 0; i < 4; ++i) snext[i] = __builtin_nontemporal_load((const f32x4*)(p.in[3] + soff + 64 * 128 + 32 * i));
;         }
;         float cs[8];
; #pragma unroll
;         for (int t = 0; t < 8; ++t) {
;             float sum = 0.f;
; #pragma unroll
;             for (int i = 0; i < 4; ++i) { const f32x4 c4 = *(const f32x4*)(Cc + t * 128 + nq * 4 + 32 * i); sum += c4[0] * s0[i][0] + c4[1] * s0[i][1] + c4[2] * s0[i][2] + c4[3] * s0[i][3]; }
	v_pk_fma_f32 v[30:31], v[62:63], v[26:27], v[30:31] op_sel_hi:[0,1,1]
	v_pk_fma_f32 v[28:29], v[62:63], v[24:25], v[28:29] op_sel_hi:[0,1,1]
	ds_read_b128 v[24:27], v73 offset:1280
	s_waitcnt lgkmcnt(0)
	v_pk_fma_f32 v[30:31], v[64:65], v[26:27], v[30:31] op_sel_hi:[0,1,1]
	v_pk_fma_f32 v[28:29], v[64:65], v[24:25], v[28:29] op_sel_hi:[0,1,1]
	ds_read_b128 v[24:27], v73 offset:1792
	s_waitcnt lgkmcnt(0)
	v_pk_fma_f32 v[30:31], v[42:43], v[26:27], v[30:31] op_sel_hi:[0,1,1]
	v_pk_fma_f32 v[28:29], v[42:43], v[24:25], v[28:29] op_sel_hi:[0,1,1]
	ds_read_b128 v[24:27], v73 offset:2304
	s_waitcnt lgkmcnt(0)
	v_pk_fma_f32 v[30:31], v[60:61], v[26:27], v[30:31] op_sel_hi:[0,1,1]
	v_pk_fma_f32 v[28:29], v[60:61], v[24:25], v[28:29] op_sel_hi:[0,1,1]
	ds_read_b128 v[24:27], v73 offset:2816
	s_waitcnt lgkmcnt(0)
	v_pk_fma_f32 v[30:31], v[40:41], v[26:27], v[30:31] op_sel_hi:[0,1,1]
	v_pk_fma_f32 v[28:29], v[40:41], v[24:25], v[28:29] op_sel_hi:[0,1,1]
	ds_read_b128 v[24:27], v73 offset:3328
	s_waitcnt lgkmcnt(0)
	v_pk_fma_f32 v[30:31], v[38:39], v[26:27], v[30:31] op_sel_hi:[0,1,1]
	v_pk_fma_f32 v[28:29], v[38:39], v[24:25], v[28:29] op_sel_hi:[0,1,1]
	ds_read_b128 v[24:27], v73 offset:3840
	s_waitcnt lgkmcnt(0)
	v_pk_fma_f32 v[26:27], v[36:37], v[26:27], v[30:31] op_sel_hi:[0,1,1]
	v_pk_fma_f32 v[24:25], v[36:37], v[24:25], v[28:29] op_sel_hi:[0,1,1]
	global_store_dwordx4 v[32:33], v[24:27], off nt
	ds_read_b128 v[24:27], v73 offset:384
	s_waitcnt vmcnt(4)
	v_mov_b64_e32 v[30:31], v[14:15]
	v_mov_b64_e32 v[28:29], v[12:13]
	s_waitcnt lgkmcnt(0)
	v_pk_mul_f32 v[26:27], v[66:67], v[26:27] op_sel_hi:[0,1]
	v_pk_mul_f32 v[24:25], v[66:67], v[24:25] op_sel_hi:[0,1]
	v_pk_fma_f32 v[24:25], v[20:21], v[68:69], v[24:25] op_sel_hi:[1,0,1]
	v_pk_fma_f32 v[26:27], v[22:23], v[68:69], v[26:27] op_sel_hi:[1,0,1]
	ds_read_b128 v[20:23], v73 offset:896
	s_waitcnt lgkmcnt(0)
	v_pk_fma_f32 v[26:27], v[62:63], v[22:23], v[26:27] op_sel_hi:[0,1,1]
	v_pk_fma_f32 v[24:25], v[62:63], v[20:21], v[24:25] op_sel_hi:[0,1,1]
	ds_read_b128 v[20:23], v73 offset:1408
	s_waitcnt lgkmcnt(0)
	v_pk_fma_f32 v[26:27], v[64:65], v[22:23], v[26:27] op_sel_hi:[0,1,1]
	v_pk_fma_f32 v[24:25], v[64:65], v[20:21], v[24:25] op_sel_hi:[0,1,1]
	ds_read_b128 v[20:23], v73 offset:1920
	s_waitcnt lgkmcnt(0)
	v_pk_fma_f32 v[26:27], v[42:43], v[22:23], v[26:27] op_sel_hi:[0,1,1]
	v_pk_fma_f32 v[24:25], v[42:43], v[20:21], v[24:25] op_sel_hi:[0,1,1]
	ds_read_b128 v[20:23], v73 offset:2432
	s_waitcnt lgkmcnt(0)
	v_pk_fma_f32 v[26:27], v[60:61], v[22:23], v[26:27] op_sel_hi:[0,1,1]
	v_pk_fma_f32 v[24:25], v[60:61], v[20:21], v[24:25] op_sel_hi:[0,1,1]
	ds_read_b128 v[20:23], v73 offset:2944
	s_waitcnt lgkmcnt(0)
	v_pk_fma_f32 v[26:27], v[40:41], v[22:23], v[26:27] op_sel_hi:[0,1,1]
	v_pk_fma_f32 v[24:25], v[40:41], v[20:21], v[24:25] op_sel_hi:[0,1,1]
	ds_read_b128 v[20:23], v73 offset:3456
	s_waitcnt lgkmcnt(0)
	v_pk_fma_f32 v[26:27], v[38:39], v[22:23], v[26:27] op_sel_hi:[0,1,1]
	v_pk_fma_f32 v[24:25], v[38:39], v[20:21], v[24:25] op_sel_hi:[0,1,1]
	ds_read_b128 v[20:23], v73 offset:3968
	s_waitcnt lgkmcnt(0)
	v_pk_fma_f32 v[22:23], v[36:37], v[22:23], v[26:27] op_sel_hi:[0,1,1]
	v_pk_fma_f32 v[20:21], v[36:37], v[20:21], v[24:25] op_sel_hi:[0,1,1]
	global_store_dwordx4 v[32:33], v[20:23], off offset:128 nt
	v_mov_b64_e32 v[34:35], v[18:19]
	v_mov_b64_e32 v[26:27], v[10:11]
	v_mov_b64_e32 v[22:23], v[6:7]
	v_mov_b64_e32 v[32:33], v[16:17]
	v_mov_b64_e32 v[24:25], v[8:9]
	v_mov_b64_e32 v[20:21], v[4:5]
	s_cbranch_scc1 .LBB0_694
.LBB0_678:
	global_load_dword v4, v149, s[88:89]
	global_load_dword v60, v149, s[86:87]
	global_load_ushort v118, v[52:53], off
	s_add_i32 s36, s33, 0
	v_mov_b32_e32 v5, s36
	ds_read_b128 v[40:43], v5
	ds_read_b128 v[36:39], v5 offset:16
	s_mov_b32 s36, 0x8000
	v_add_u32_e32 v94, 0, v85
	v_mov_b32_e32 v111, 0
	v_mov_b32_e32 v112, 0
	s_waitcnt vmcnt(2)
	v_mul_f32_e32 v4, 0x3fb8aa3b, v4
	v_exp_f32_e32 v4, v4
	s_waitcnt lgkmcnt(1)
	v_fma_f32 v93, -v4, v40, 0
	v_fma_f32 v92, -v4, v41, v93
	v_fma_f32 v91, -v4, v42, v92
	v_fma_f32 v90, -v4, v43, v91
	s_waitcnt lgkmcnt(0)
	v_fma_f32 v89, -v4, v36, v90
	v_fma_f32 v88, -v4, v37, v89
	v_fma_f32 v86, -v4, v38, v88
	v_fma_f32 v87, -v4, v39, v86
	v_lshl_add_u64 v[4:5], v[56:57], 0, s[92:93]
	v_add_co_u32_e64 v4, s[36:37], s36, v4
	s_nop 1
	v_addc_co_u32_e64 v5, s[36:37], 0, v5, s[36:37]
	global_load_dwordx4 v[16:19], v[4:5], off nt
	global_load_dwordx4 v[12:15], v[4:5], off offset:128 nt
	global_load_dwordx4 v[8:11], v[4:5], off offset:256 nt
	s_nop 0
	global_load_dwordx4 v[4:7], v[4:5], off offset:384 nt
	ds_read_b128 v[62:65], v83 offset:4096
	s_waitcnt lgkmcnt(0)
	v_mul_f32_e32 v61, v33, v63
	v_fmac_f32_e32 v61, v32, v62
	v_fmac_f32_e32 v61, v34, v64
	v_fmac_f32_e32 v61, v35, v65
	ds_read_b128 v[62:65], v83 offset:4224
	v_add_f32_e32 v61, 0, v61
	s_waitcnt lgkmcnt(0)
	v_mul_f32_e32 v63, v29, v63
	v_fmac_f32_e32 v63, v28, v62
	v_fmac_f32_e32 v63, v30, v64
	v_fmac_f32_e32 v63, v31, v65
	v_add_f32_e32 v61, v61, v63
	ds_read_b128 v[62:65], v83 offset:4352
	s_waitcnt lgkmcnt(0)
	v_mul_f32_e32 v63, v25, v63
	v_fmac_f32_e32 v63, v24, v62
	v_fmac_f32_e32 v63, v26, v64
	v_fmac_f32_e32 v63, v27, v65
	v_add_f32_e32 v61, v61, v63
	ds_read_b128 v[62:65], v83 offset:4480
	s_waitcnt lgkmcnt(0)
	v_mul_f32_e32 v63, v21, v63
	v_fmac_f32_e32 v63, v20, v62
	v_fmac_f32_e32 v63, v22, v64
	v_fmac_f32_e32 v63, v23, v65
	v_add_f32_e32 v61, v61, v63
	ds_bpermute_b32 v62, v82, v61
	s_waitcnt lgkmcnt(0)
	v_add_f32_e32 v61, v61, v62
	ds_bpermute_b32 v62, v81, v61
	s_waitcnt lgkmcnt(0)
	v_add_f32_e32 v61, v61, v62
	ds_read_b128 v[62:65], v83 offset:4608
	ds_bpermute_b32 v67, v80, v61
	s_waitcnt lgkmcnt(1)
; __device__ __forceinline__ void sample_ssd(const Params& p, unsigned char* smem, int job) {
;     ...
;         for (int t = 0; t < 8; ++t) {
;             float sum = 0.f;
; #pragma unroll
;             for (int i = 0; i < 4; ++i) { const f32x4 c4 = *(const f32x4*)(Cc + t * 128 + nq * 4 + 32 * i); sum += c4[0] * s0[i][0] + c4[1] * s0[i][1] + c4[2] * s0[i][2] + c4[3] * s0[i][3]; }
;             sum += __shfl_xor(sum, 1); sum += __shfl_xor(sum, 2); sum += __shfl_xor(sum, 4);
;             cs[t] = sum;
;         }
	v_mul_f32_e32 v63, v33, v63
	v_fmac_f32_e32 v63, v32, v62
	v_fmac_f32_e32 v63, v34, v64
	v_fmac_f32_e32 v63, v35, v65
	v_add_f32_e32 v66, 0, v63
	ds_read_b128 v[62:65], v83 offset:4736
	s_waitcnt lgkmcnt(0)
	v_mul_f32_e32 v63, v29, v63
	v_fmac_f32_e32 v63, v28, v62
	v_fmac_f32_e32 v63, v30, v64
	v_fmac_f32_e32 v63, v31, v65
	v_add_f32_e32 v66, v66, v63
	ds_read_b128 v[62:65], v83 offset:4864
	s_waitcnt lgkmcnt(0)
	v_mul_f32_e32 v63, v25, v63
	v_fmac_f32_e32 v63, v24, v62
	v_fmac_f32_e32 v63, v26, v64
	v_fmac_f32_e32 v63, v27, v65
	v_add_f32_e32 v66, v66, v63
	ds_read_b128 v[62:65], v83 offset:4992
	s_waitcnt lgkmcnt(0)
	v_mul_f32_e32 v63, v21, v63
	v_fmac_f32_e32 v63, v20, v62
	v_fmac_f32_e32 v63, v22, v64
	v_fmac_f32_e32 v63, v23, v65
	v_add_f32_e32 v62, v66, v63
	ds_bpermute_b32 v63, v82, v62
	s_waitcnt lgkmcnt(0)
	v_add_f32_e32 v62, v62, v63
	ds_bpermute_b32 v63, v81, v62
	s_waitcnt lgkmcnt(0)
	v_add_f32_e32 v72, v62, v63
	ds_read_b128 v[62:65], v83 offset:5120
	ds_bpermute_b32 v95, v80, v72
	s_waitcnt lgkmcnt(1)
	v_mul_f32_e32 v63, v33, v63
	v_fmac_f32_e32 v63, v32, v62
	v_fmac_f32_e32 v63, v34, v64
	v_fmac_f32_e32 v63, v35, v65
	v_add_f32_e32 v66, 0, v63
	ds_read_b128 v[62:65], v83 offset:5248
	s_waitcnt lgkmcnt(0)
	v_mul_f32_e32 v63, v29, v63
	v_fmac_f32_e32 v63, v28, v62
	v_fmac_f32_e32 v63, v30, v64
	v_fmac_f32_e32 v63, v31, v65
	v_add_f32_e32 v66, v66, v63
	ds_read_b128 v[62:65], v83 offset:5376
	s_waitcnt lgkmcnt(0)
	v_mul_f32_e32 v63, v25, v63
	v_fmac_f32_e32 v63, v24, v62
	v_fmac_f32_e32 v63, v26, v64
	v_fmac_f32_e32 v63, v27, v65
	v_add_f32_e32 v66, v66, v63
	ds_read_b128 v[62:65], v83 offset:5504
	s_waitcnt lgkmcnt(0)
	v_mul_f32_e32 v63, v21, v63
	v_fmac_f32_e32 v63, v20, v62
	v_fmac_f32_e32 v63, v22, v64
	v_fmac_f32_e32 v63, v23, v65
	v_add_f32_e32 v62, v66, v63
	ds_bpermute_b32 v63, v82, v62
	s_waitcnt lgkmcnt(0)
	v_add_f32_e32 v62, v62, v63
	ds_bpermute_b32 v63, v81, v62
	s_waitcnt lgkmcnt(0)
	v_add_f32_e32 v96, v62, v63
	ds_read_b128 v[62:65], v83 offset:5632
	ds_bpermute_b32 v97, v80, v96
	s_waitcnt lgkmcnt(1)
	v_mul_f32_e32 v63, v33, v63
	v_fmac_f32_e32 v63, v32, v62
	v_fmac_f32_e32 v63, v34, v64
	v_fmac_f32_e32 v63, v35, v65
	v_add_f32_e32 v66, 0, v63
	ds_read_b128 v[62:65], v83 offset:5760
	s_waitcnt lgkmcnt(0)
	v_mul_f32_e32 v63, v29, v63
	v_fmac_f32_e32 v63, v28, v62
	v_fmac_f32_e32 v63, v30, v64
	v_fmac_f32_e32 v63, v31, v65
	v_add_f32_e32 v66, v66, v63
	ds_read_b128 v[62:65], v83 offset:5888
	s_waitcnt lgkmcnt(0)
	v_mul_f32_e32 v63, v25, v63
	v_fmac_f32_e32 v63, v24, v62
	v_fmac_f32_e32 v63, v26, v64
	v_fmac_f32_e32 v63, v27, v65
	v_add_f32_e32 v66, v66, v63
	ds_read_b128 v[62:65], v83 offset:6016
	s_waitcnt lgkmcnt(0)
	v_mul_f32_e32 v63, v21, v63
	v_fmac_f32_e32 v63, v20, v62
	v_fmac_f32_e32 v63, v22, v64
	v_fmac_f32_e32 v63, v23, v65
	v_add_f32_e32 v62, v66, v63
	ds_bpermute_b32 v63, v82, v62
	s_waitcnt lgkmcnt(0)
	v_add_f32_e32 v62, v62, v63
	ds_bpermute_b32 v63, v81, v62
	s_waitcnt lgkmcnt(0)
	v_add_f32_e32 v98, v62, v63
	ds_read_b128 v[62:65], v83 offset:6144
	ds_bpermute_b32 v99, v80, v98
	s_waitcnt lgkmcnt(1)
	v_mul_f32_e32 v63, v33, v63
	v_fmac_f32_e32 v63, v32, v62
	v_fmac_f32_e32 v63, v34, v64
	v_fmac_f32_e32 v63, v35, v65
	v_add_f32_e32 v66, 0, v63
	ds_read_b128 v[62:65], v83 offset:6272
	s_waitcnt lgkmcnt(0)
	v_mul_f32_e32 v63, v29, v63
	v_fmac_f32_e32 v63, v28, v62
	v_fmac_f32_e32 v63, v30, v64
	v_fmac_f32_e32 v63, v31, v65
	v_add_f32_e32 v66, v66, v63
	ds_read_b128 v[62:65], v83 offset:6400
	s_waitcnt lgkmcnt(0)
	v_mul_f32_e32 v63, v25, v63
	v_fmac_f32_e32 v63, v24, v62
	v_fmac_f32_e32 v63, v26, v64
	v_fmac_f32_e32 v63, v27, v65
	v_add_f32_e32 v66, v66, v63
	ds_read_b128 v[62:65], v83 offset:6528
	s_waitcnt lgkmcnt(0)
	v_mul_f32_e32 v63, v21, v63
	v_fmac_f32_e32 v63, v20, v62
	v_fmac_f32_e32 v63, v22, v64
	v_fmac_f32_e32 v63, v23, v65
	v_add_f32_e32 v62, v66, v63
	ds_bpermute_b32 v63, v82, v62
	s_waitcnt lgkmcnt(0)
; __device__ __forceinline__ void sample_ssd(const Params& p, unsigned char* smem, int job) {
;     ...
;         for (int t = 0; t < 8; ++t) {
;             float sum = 0.f;
; #pragma unroll
;             for (int i = 0; i < 4; ++i) { const f32x4 c4 = *(const f32x4*)(Cc + t * 128 + nq * 4 + 32 * i); sum += c4[0] * s0[i][0] + c4[1] * s0[i][1] + c4[2] * s0[i][2] + c4[3] * s0[i][3]; }
;             sum += __shfl_xor(sum, 1); sum += __shfl_xor(sum, 2); sum += __shfl_xor(sum, 4);
;             cs[t] = sum;
;         }
;         float ycs = 0.f, ct = 0.f;
; #pragma unroll
;         for (int t = 0; t < 8; ++t) { ycs = (nq == t) ? cs[t] : ycs; ct = (nq == t) ? cum[t] : ct; }
;         float y = __expf(ct) * ycs, xt = 0.f;
; #pragma unroll
;         for (int s = 0; s < 8; ++s) {
;             const float xs = xall[s * 1024 + hh * 64 + pp];
;             const float term = (s <= nq) ? G[nq * 8 + s] * __expf(ct - cum[s]) * dtv[s] * xs : 0.f;
;             y += term; xt = (s == nq) ? xs : xt;
	v_add_f32_e32 v62, v62, v63
	ds_bpermute_b32 v63, v81, v62
	s_waitcnt lgkmcnt(0)
	v_add_f32_e32 v100, v62, v63
	ds_read_b128 v[62:65], v83 offset:6656
	ds_bpermute_b32 v101, v80, v100
	s_waitcnt lgkmcnt(1)
	v_mul_f32_e32 v63, v33, v63
	v_fmac_f32_e32 v63, v32, v62
	v_fmac_f32_e32 v63, v34, v64
	v_fmac_f32_e32 v63, v35, v65
	v_add_f32_e32 v66, 0, v63
	ds_read_b128 v[62:65], v83 offset:6784
	s_waitcnt lgkmcnt(0)
	v_mul_f32_e32 v63, v29, v63
	v_fmac_f32_e32 v63, v28, v62
	v_fmac_f32_e32 v63, v30, v64
	v_fmac_f32_e32 v63, v31, v65
	v_add_f32_e32 v66, v66, v63
	ds_read_b128 v[62:65], v83 offset:6912
	s_waitcnt lgkmcnt(0)
	v_mul_f32_e32 v63, v25, v63
	v_fmac_f32_e32 v63, v24, v62
	v_fmac_f32_e32 v63, v26, v64
	v_fmac_f32_e32 v63, v27, v65
	v_add_f32_e32 v66, v66, v63
	ds_read_b128 v[62:65], v83 offset:7040
	s_waitcnt lgkmcnt(0)
	v_mul_f32_e32 v63, v21, v63
	v_fmac_f32_e32 v63, v20, v62
	v_fmac_f32_e32 v63, v22, v64
	v_fmac_f32_e32 v63, v23, v65
	v_add_f32_e32 v62, v66, v63
	ds_bpermute_b32 v63, v82, v62
	s_waitcnt lgkmcnt(0)
	v_add_f32_e32 v62, v62, v63
	ds_bpermute_b32 v63, v81, v62
	s_waitcnt lgkmcnt(0)
	v_add_f32_e32 v102, v62, v63
	ds_read_b128 v[62:65], v83 offset:7168
	ds_bpermute_b32 v103, v80, v102
	s_waitcnt lgkmcnt(1)
	v_mul_f32_e32 v63, v33, v63
	v_fmac_f32_e32 v63, v32, v62
	v_fmac_f32_e32 v63, v34, v64
	v_fmac_f32_e32 v63, v35, v65
	v_add_f32_e32 v66, 0, v63
	ds_read_b128 v[62:65], v83 offset:7296
	s_waitcnt lgkmcnt(0)
	v_mul_f32_e32 v63, v29, v63
	v_fmac_f32_e32 v63, v28, v62
	v_fmac_f32_e32 v63, v30, v64
	v_fmac_f32_e32 v63, v31, v65
	v_add_f32_e32 v66, v66, v63
	ds_read_b128 v[62:65], v83 offset:7424
	s_waitcnt lgkmcnt(0)
	v_mul_f32_e32 v63, v25, v63
	v_fmac_f32_e32 v63, v24, v62
	v_fmac_f32_e32 v63, v26, v64
	v_fmac_f32_e32 v63, v27, v65
	v_add_f32_e32 v66, v66, v63
	ds_read_b128 v[62:65], v83 offset:7552
	s_waitcnt lgkmcnt(0)
	v_mul_f32_e32 v63, v21, v63
	v_fmac_f32_e32 v63, v20, v62
	v_fmac_f32_e32 v63, v22, v64
	v_fmac_f32_e32 v63, v23, v65
	v_add_f32_e32 v62, v66, v63
	ds_bpermute_b32 v63, v82, v62
	s_waitcnt lgkmcnt(0)
	v_add_f32_e32 v62, v62, v63
	ds_bpermute_b32 v63, v81, v62
	s_waitcnt lgkmcnt(0)
	v_add_f32_e32 v104, v62, v63
	ds_read_b128 v[62:65], v83 offset:7680
	ds_bpermute_b32 v105, v80, v104
	s_waitcnt lgkmcnt(1)
	v_mul_f32_e32 v63, v33, v63
	v_fmac_f32_e32 v63, v32, v62
	v_fmac_f32_e32 v63, v34, v64
	v_fmac_f32_e32 v63, v35, v65
	v_add_f32_e32 v66, 0, v63
	ds_read_b128 v[62:65], v83 offset:7808
	s_waitcnt lgkmcnt(0)
	v_mul_f32_e32 v63, v29, v63
	v_fmac_f32_e32 v63, v28, v62
	v_fmac_f32_e32 v63, v30, v64
	v_fmac_f32_e32 v63, v31, v65
	v_add_f32_e32 v66, v66, v63
	ds_read_b128 v[62:65], v83 offset:7936
	s_waitcnt lgkmcnt(0)
	v_mul_f32_e32 v63, v25, v63
	v_fmac_f32_e32 v63, v24, v62
	v_fmac_f32_e32 v63, v26, v64
	v_fmac_f32_e32 v63, v27, v65
	v_add_f32_e32 v66, v66, v63
	ds_read_b128 v[62:65], v83 offset:8064
	s_waitcnt lgkmcnt(0)
	v_mul_f32_e32 v63, v21, v63
	v_fmac_f32_e32 v63, v20, v62
	v_fmac_f32_e32 v63, v22, v64
	v_fmac_f32_e32 v63, v23, v65
	v_add_f32_e32 v62, v66, v63
	ds_bpermute_b32 v63, v82, v62
	s_waitcnt lgkmcnt(0)
	v_add_f32_e32 v62, v62, v63
	ds_bpermute_b32 v63, v81, v62
	s_waitcnt lgkmcnt(0)
	v_add_f32_e32 v107, v62, v63
	v_cndmask_b32_e64 v62, 0, v93, s[4:5]
	v_cndmask_b32_e64 v62, v62, v92, s[6:7]
	v_cndmask_b32_e64 v62, v62, v91, s[8:9]
	v_cndmask_b32_e64 v62, v62, v90, s[10:11]
	v_cndmask_b32_e64 v62, v62, v89, s[12:13]
	v_cndmask_b32_e64 v62, v62, v88, s[14:15]
	v_cndmask_b32_e64 v62, v62, v86, s[16:17]
	ds_bpermute_b32 v108, v80, v107
	v_cndmask_b32_e64 v106, v62, v87, s[18:19]
	ds_read2st64_b32 v[62:63], v94 offset1:16
	ds_read_b32 v109, v79 offset:40960
	s_and_saveexec_b64 s[36:37], s[22:23]
	s_cbranch_execz .LBB0_680
	v_sub_f32_e32 v64, v106, v92
	v_mul_f32_e32 v64, 0x3fb8aa3b, v64
	ds_read_b32 v65, v79 offset:40964
	v_exp_f32_e32 v64, v64
	s_waitcnt lgkmcnt(0)
	v_mul_f32_e32 v64, v64, v65
	v_mul_f32_e32 v64, v41, v64
	v_mul_f32_e32 v112, v63, v64

; __device__ __forceinline__ unsigned pack2(float lo, float hi) { unsigned r; asm("v_cvt_pk_bf16_f32 %0, %1, %2" : "=v"(r) : "v"(lo), "v"(hi)); return r; }
; __device__ __forceinline__ float bf2f(bf16_t h) { return __uint_as_float((unsigned)h << 16); }
; __device__ __forceinline__ float silu_f(float x) { return x * sigm_f(x); }
; __device__ __forceinline__ void sample_ssd(const Params& p, unsigned char* smem, int job) {
;     ...
;             y += term; xt = (s == nq) ? xs : xt;
;         }
;         y += D_h * xt;
;         const float z = bf2f(U[(size_t)(rowb + nq) * N1P + UC_Z + h * 64 + pp]);
;         y *= silu_f(z);
;         { const unsigned pk = pack2(y, 0.f); MIX[(size_t)(rowb + nq) * MIXW + h * 64 + pp] = (bf16_t)(pk & 0xffffu); }
;         float sq = y * y; sq += __shfl_xor(sq, 8); sq += __shfl_xor(sq, 16); sq += __shfl_xor(sq, 32);
;         if (lane < 8) ssqp[(hh * 8 + wid) * 8 + lane] = sq;
.LBB0_692:
	s_or_b64 exec, exec, s[36:37]
	v_add_f32_e32 v61, v61, v67
	v_add_f32_e32 v72, v72, v95
	v_cndmask_b32_e64 v61, 0, v61, s[4:5]
	v_add_f32_e32 v95, v96, v97
	v_cndmask_b32_e64 v61, v61, v72, s[6:7]
	v_add_f32_e32 v96, v98, v99
	v_cndmask_b32_e64 v61, v61, v95, s[8:9]
	v_add_f32_e32 v97, v100, v101
	v_cndmask_b32_e64 v61, v61, v96, s[10:11]
	v_mul_f32_e32 v67, 0x3fb8aa3b, v106
	v_add_f32_e32 v98, v102, v103
	v_cndmask_b32_e64 v61, v61, v97, s[12:13]
	v_exp_f32_e32 v67, v67
	v_add_f32_e32 v99, v104, v105
	v_cndmask_b32_e64 v61, v61, v98, s[14:15]
	v_add_f32_e32 v100, v107, v108
	v_cndmask_b32_e64 v61, v61, v99, s[16:17]
	v_cndmask_b32_e64 v61, v61, v100, s[18:19]
	v_mul_f32_e32 v61, v67, v61
	v_sub_f32_e32 v67, v106, v93
	v_mul_f32_e32 v67, 0x3fb8aa3b, v67
	v_exp_f32_e32 v67, v67
	s_nop 0
	v_mul_f32_e32 v67, v67, v109
	v_mul_f32_e32 v67, v40, v67
	v_fmac_f32_e32 v61, v62, v67
	v_add_f32_e32 v61, v61, v112
	v_add_f32_e32 v61, v61, v113
	v_add_f32_e32 v61, v61, v111
	v_add_f32_e32 v61, v61, v115
	v_add_f32_e32 v61, v61, v114
	v_add_f32_e32 v61, v61, v117
	v_add_f32_e32 v72, v61, v116
	s_waitcnt vmcnt(4)
	v_mov_b32_e32 v61, v118
	v_lshlrev_b32_e32 v95, 16, v61
	v_max_f32_e64 v61, -v95, -v95
	v_min_f32_e32 v61, 0x42a00000, v61
	v_mul_f32_e32 v61, 0x3fb8aa3b, v61
	v_exp_f32_e32 v61, v61
	s_nop 0
	v_add_f32_e32 v67, 1.0, v61
	v_rcp_f32_e32 v61, v67
	s_nop 0
	v_fma_f32 v67, -v67, v61, 2.0
	v_pk_fma_f32 v[96:97], v[60:61], v[66:67], v[72:73]
	v_mul_f32_e32 v60, v61, v67
	v_mul_f32_e32 v60, v60, v95
	v_mul_f32_e32 v60, v96, v60
	v_cvt_pk_bf16_f32 v61, v60, v149
	global_store_short v[54:55], v61, off
	v_mul_f32_e32 v61, v60, v60
	ds_bpermute_b32 v61, v77, v61
	s_waitcnt lgkmcnt(0)
	v_fmac_f32_e32 v61, v60, v60
	ds_bpermute_b32 v60, v78, v61
	s_waitcnt lgkmcnt(0)
	v_add_f32_e32 v60, v61, v60
	ds_bpermute_b32 v61, v76, v60
	s_and_saveexec_b64 s[36:37], s[0:1]
	s_cbranch_execz .LBB0_677
	v_add_u32_e32 v62, 0, v84
	s_waitcnt lgkmcnt(0)
	v_add_f32_e32 v60, v60, v61
	ds_write_b32 v62, v60
	ds_read2st64_b32 v[62:63], v94 offset1:16
	ds_read2st64_b32 v[64:65], v94 offset0:32 offset1:48
	ds_read2st64_b32 v[68:69], v94 offset0:64 offset1:80
	ds_read2st64_b32 v[70:71], v94 offset0:96 offset1:112
	s_branch .LBB0_677
